# phase I (mixers): one static s_setprio 1 for waves 4-7, reset at phase end
# baseline (speedup 1.0000x reference)
.LBB0_754:
	v_mov_b32_e32 v0, v1
	s_waitcnt lgkmcnt(0)
	s_barrier
	v_readlane_b32 s98, v248, 5
	s_nop 3
	s_cmp_ge_u32 s98, 0x100
	s_cbranch_scc0 .Lprio_skip_i
	s_setprio 1
.Lprio_skip_i:
	v_readlane_b32 s0, v248, 5
	v_mbcnt_lo_u32_b32 v0, -1, v0
	v_mbcnt_hi_u32_b32 v197, -1, v0
	v_readlane_b32 s8, v247, 45
	v_add_u32_e32 v196, s0, v197
	v_readlane_b32 s48, v248, 10
	s_lshl_b32 s0, s8, 8
	v_readlane_b32 s49, v248, 11
	s_lshl_b64 s[6:7], s[0:1], 2
	s_add_u32 s0, s48, s6
	s_addc_u32 s7, s49, s7
	s_add_u32 s6, s0, 0x8000
	s_addc_u32 s7, s7, 0
	s_add_u32 s22, s48, 0x2de00000
	s_addc_u32 s23, s49, 0
	s_add_u32 s24, s48, 0x2e700000
	s_addc_u32 s25, s49, 0
	s_add_u32 s26, s48, 0x18e00000
	s_addc_u32 s27, s49, 0
	s_add_u32 s28, s48, 0x3a700000
	s_addc_u32 s29, s49, 0
	s_lshl_b32 s0, s8, 10
	s_add_u32 s30, s48, 0x31200000
	v_cmp_eq_u32_e64 s[10:11], 0, v196
	s_addc_u32 s31, s49, 0
	s_lshl_b64 s[12:13], s[0:1], 2
	s_branch .LBB0_757

; __device__ __forceinline__ unsigned xb_add(unsigned* p, unsigned v) { return __hip_atomic_fetch_add(p, v, __ATOMIC_RELAXED, __HIP_MEMORY_SCOPE_AGENT); }
; __device__ __forceinline__ void xcd_barrier(const XcdBarrier& b) {
;     asm volatile("s_waitcnt vmcnt(0)" ::: "memory");
;     __syncthreads();
;     if (b.w0 == 0 && __builtin_amdgcn_mbcnt_hi(~0u, __builtin_amdgcn_mbcnt_lo(~0u, b.zz)) == 0u) {
;         unsigned* bar = b.bar;
;         __builtin_amdgcn_s_waitcnt(0);
;         unsigned nloc = b.st[0], nx = b.st[1];
;         if (nloc == 0u) { xcd_barrier_complete(bar, b.x, nloc, nx); b.st[0] = nloc; b.st[1] = nx; }
;         const unsigned old = xb_add(&bar[XB_XSUB(b.x)], 1u);
;         const unsigned gen = old / nloc;
.LBB0_833:
	s_setprio 0
	v_readlane_b32 s6, v248, 2
	v_readlane_b32 s0, v248, 4
	v_readlane_b32 s7, v248, 3
	v_mov_b32_e32 v0, v1
	s_waitcnt vmcnt(0)
	v_readlane_b32 s8, v246, 7
	v_readlane_b32 s9, v246, 8
	s_and_b64 vcc, exec, s[8:9]
	s_barrier
	s_cbranch_vccnz .LBB0_887
	v_mbcnt_lo_u32_b32 v0, -1, v0
	v_mbcnt_hi_u32_b32 v0, -1, v0
	v_cmp_eq_u32_e32 vcc, 0, v0
	s_and_saveexec_b64 s[8:9], vcc
	s_cbranch_execz .LBB0_886
	v_readlane_b32 s10, v247, 38
	s_waitcnt vmcnt(0) expcnt(0) lgkmcnt(0)
	s_nop 0
	v_mov_b32_e32 v0, s10
	ds_read_b32 v3, v0
	v_readlane_b32 s10, v247, 39
	s_waitcnt lgkmcnt(0)
	v_cmp_ne_u32_e32 vcc, 0, v3
	v_mov_b32_e32 v0, s10
	ds_read_b32 v2, v0
	s_cbranch_vccnz .LBB0_850
	v_readlane_b32 s10, v248, 0
	v_readlane_b32 s11, v248, 1
	s_load_dwordx2 s[14:15], s[10:11], 0x4
	s_add_u32 s10, s6, 0x1000
	s_addc_u32 s11, s7, 0
	s_add_u32 s12, s6, 0x1100
	s_addc_u32 s13, s7, 0
	s_waitcnt lgkmcnt(0)
	s_mul_i32 s24, s14, s50
	s_add_u32 s14, s6, 0x1200
	s_mul_i32 s24, s24, s15
	s_addc_u32 s15, s7, 0
	s_add_u32 s16, s6, 0x1300
	s_addc_u32 s17, s7, 0
	s_mov_b32 s25, 1
	s_branch .LBB0_838
